# P3 channel-DFT items: second k-slice's LDS-DMA loads issued together with the first slice's, before the first wait (both LDS stages in flight at item start)
# speedup vs baseline: 1.0032x; 1.0021x over previous
; DI void wait_vm0() { asm volatile("s_waitcnt vmcnt(0)" ::: "memory"); }
; DI void bar_() { __builtin_amdgcn_s_barrier(); }
; #define GLDS(gp, lp) __builtin_amdgcn_global_load_lds((const unsigned*)(gp), (__attribute__((address_space(3))) unsigned*)(lp), 16, 0, 0)
; template <int TM, int TN, int WM, int WN, bool SUMSQ, int NST, class AF, class BF, class AFN, class BFN>
; DI void gemm8x(f32x16 (&acc)[TM][TN], AF arow, BF brow, int K, char* smem, float& sumsq, bool pre, bool hasNext, AFN arowN, BFN browN) {
;     ...
;   if (!pre) {
;     char* l_ = smem + t * 16; char* m_ = l_ + RA * LDR;
;     if (a0v) GLDS(pa0, l_); if (a1v) GLDS(pa1, l_ + 8192); if (a2v) GLDS(pa2, l_ + 16384); if (a3v) GLDS(pa3, l_ + 24576);
;     if (b0v) GLDS(pb0, m_); if (b1v) GLDS(pb1, m_ + 8192); if (b2v) GLDS(pb2, m_ + 16384); if (b3v) GLDS(pb3, m_ + 24576);
;   }
;   if (NST == 3) {
;     char* l_ = smem + STAGE + t * 16; char* m_ = l_ + RA * LDR;
;     GLDS(pa0 + 64, l_); GLDS(pa1 + 64, l_ + 8192); GLDS(pa2 + 64, l_ + 16384); GLDS(pa3 + 64, l_ + 24576);
;     GLDS(pb0 + 64, m_); GLDS(pb1 + 64, m_ + 8192);
;     asm volatile("s_waitcnt vmcnt(6)" ::: "memory");
;   } else wait_vm0();
;   bar_();
; DI void phase3(const Params& p, char* smem) {
;     ...
;       gemm8<4, 2, 2, 4, false>(acc, [&](int row) { return Fb + (size_t)row * 512; }, [&](int row) { return Tb + (size_t)row * 128; }, 128, smem, dummy);
.LBB0_339:
	s_or_b64 exec, exec, s[10:11]
	v_ashrrev_i32_e32 v0, 6, v8
	v_lshrrev_b32_e32 v1, 31, v8
	v_add_u32_e32 v1, v0, v1
	v_and_b32_e32 v2, 0x3fffe, v1
	v_lshlrev_b32_e32 v3, 7, v8
	v_sub_u32_e32 v0, v0, v2
	v_and_b32_e32 v219, 0xf80, v3
	v_bfe_u32 v180, v8, 5, 1
	v_lshrrev_b32_e32 v2, 1, v8
	v_lshl_or_b32 v217, v0, 14, v219
	v_lshlrev_b32_e32 v0, 12, v1
	s_and_saveexec_b64 s[10:11], vcc
	s_cbranch_execz .LBB0_341
	v_add_u32_e32 v28, 0x10000, v215
	v_lshl_add_u64 v[24:25], v[24:25], 0, s[44:45]
	v_readfirstlane_b32 s15, v28
	s_mov_b32 m0, s15
	s_nop 0
	global_load_lds_dwordx4 v[24:25], off

; DI void wait_vm0() { asm volatile("s_waitcnt vmcnt(0)" ::: "memory"); }
; DI void bar_() { __builtin_amdgcn_s_barrier(); }
; #define GLDS(gp, lp) __builtin_amdgcn_global_load_lds((const unsigned*)(gp), (__attribute__((address_space(3))) unsigned*)(lp), 16, 0, 0)
; template <int TM, int TN, int WM, int WN, bool SUMSQ, int NST, class AF, class BF, class AFN, class BFN>
; DI void gemm8x(f32x16 (&acc)[TM][TN], AF arow, BF brow, int K, char* smem, float& sumsq, bool pre, bool hasNext, AFN arowN, BFN browN) {
;     ...
;   if (!pre) {
;     char* l_ = smem + t * 16; char* m_ = l_ + RA * LDR;
;     if (a0v) GLDS(pa0, l_); if (a1v) GLDS(pa1, l_ + 8192); if (a2v) GLDS(pa2, l_ + 16384); if (a3v) GLDS(pa3, l_ + 24576);
;     if (b0v) GLDS(pb0, m_); if (b1v) GLDS(pb1, m_ + 8192); if (b2v) GLDS(pb2, m_ + 16384); if (b3v) GLDS(pb3, m_ + 24576);
;   }
;   if (NST == 3) {
;     char* l_ = smem + STAGE + t * 16; char* m_ = l_ + RA * LDR;
;     GLDS(pa0 + 64, l_); GLDS(pa1 + 64, l_ + 8192); GLDS(pa2 + 64, l_ + 16384); GLDS(pa3 + 64, l_ + 24576);
;     GLDS(pb0 + 64, m_); GLDS(pb1 + 64, m_ + 8192);
;     asm volatile("s_waitcnt vmcnt(6)" ::: "memory");
;   } else wait_vm0();
;   bar_();
; DI void phase3(const Params& p, char* smem) {
;     ...
;       gemm8<4, 2, 2, 4, false>(acc, [&](int row) { return Fb + (size_t)row * 512; }, [&](int row) { return Tb + (size_t)row * 128; }, 128, smem, dummy);
.LBB0_343:
	s_or_b64 exec, exec, s[10:11]
	s_and_saveexec_b64 s[10:11], s[4:5]
	s_cbranch_execz .LBB0_345
	v_add_u32_e32 v182, 0x14000, v215
	v_lshl_add_u64 v[176:177], v[176:177], 0, s[44:45]
	v_readfirstlane_b32 s15, v182
	s_mov_b32 m0, s15
	s_nop 0
	global_load_lds_dwordx4 v[176:177], off

; #define GLDS(gp, lp) __builtin_amdgcn_global_load_lds((const unsigned*)(gp), (__attribute__((address_space(3))) unsigned*)(lp), 16, 0, 0)
; template <int TM, int TN, int WM, int WN, bool SUMSQ, int NST, class AF, class BF, class AFN, class BFN>
; DI void gemm8x(f32x16 (&acc)[TM][TN], AF arow, BF brow, int K, char* smem, float& sumsq, bool pre, bool hasNext, AFN arowN, BFN browN) {
;     ...
;     if (issue) { if (b0v) GLDS(s0, m_); if (b1v) GLDS(s1, m_ + 8192); }
.LBB0_347:
	s_or_b64 exec, exec, s[10:11]
	s_and_saveexec_b64 s[10:11], vcc
	s_cbranch_execz .LBB0_349
	v_add_u32_e32 v130, 0x18000, v215
	v_lshl_add_u64 v[128:129], v[200:201], 0, s[44:45]
	v_readfirstlane_b32 s15, v130
	s_mov_b32 m0, s15
	s_nop 0
	global_load_lds_dwordx4 v[128:129], off

; #define GLDS(gp, lp) __builtin_amdgcn_global_load_lds((const unsigned*)(gp), (__attribute__((address_space(3))) unsigned*)(lp), 16, 0, 0)
; template <int TM, int TN, int WM, int WN, bool SUMSQ, int NST, class AF, class BF, class AFN, class BFN>
; DI void gemm8x(f32x16 (&acc)[TM][TN], AF arow, BF brow, int K, char* smem, float& sumsq, bool pre, bool hasNext, AFN arowN, BFN browN) {
;     ...
;     if (issue) { if (b2v) GLDS(s2, m_ + 16384); if (b3v) GLDS(s3, m_ + 24576); }
.LBB0_351:
	s_or_b64 exec, exec, s[10:11]
	s_and_saveexec_b64 s[6:7], s[4:5]
	s_cbranch_execz .LBB0_353
	v_add_u32_e32 v130, 0x1c000, v215
	v_lshl_add_u64 v[128:129], v[196:197], 0, s[44:45]
	v_readfirstlane_b32 s4, v130
	s_mov_b32 m0, s4
	s_nop 0
	global_load_lds_dwordx4 v[128:129], off

; DI void wait_vm0() { asm volatile("s_waitcnt vmcnt(0)" ::: "memory"); }
; DI void bar_() { __builtin_amdgcn_s_barrier(); }
; #define GLDS(gp, lp) __builtin_amdgcn_global_load_lds((const unsigned*)(gp), (__attribute__((address_space(3))) unsigned*)(lp), 16, 0, 0)
; #define SB_ __builtin_amdgcn_sched_barrier(0)
; template <int TM, int TN, int WM, int WN, bool SUMSQ, int NST, class AF, class BF, class AFN, class BFN>
; DI void gemm8x(f32x16 (&acc)[TM][TN], AF arow, BF brow, int K, char* smem, float& sumsq, bool pre, bool hasNext, AFN arowN, BFN browN) {
;     ...
;   } else wait_vm0();
;   bar_();
;   const int nk = K >> 6;
;   const int sw = (r >> 1) & 7;
;   const int aoff = (wm * TM * 32 + r) * LDR, boff = RA * LDR + (wn * TN * 32 + r) * LDR;
;   auto compute = [&](const char* cur, char* nxt, bool issue, const bf16_t* q0, const bf16_t* q1, const bf16_t* q2, const bf16_t* q3,
;                      const bf16_t* s0, const bf16_t* s1, const bf16_t* s2, const bf16_t* s3) {
;     const char* As = cur + aoff;
;     const char* Bs = cur + boff;
;     char* l_ = nxt + t * 16; char* m_ = l_ + RA * LDR;
;     bf16x8 a0[TM], b0[TN], a1[TM], b1[TN];
;     ...
;     LOADF(a0, b0, 0);
;     LOADF(a1, b1, 1);
;     SB_;
;     if (issue) { if (a0v) GLDS(q0, l_); if (a1v) GLDS(q1, l_ + 8192); }
;     SB_;
;     __builtin_amdgcn_s_setprio(1);
;     MMF(a0, b0);
;     LOADF(a0, b0, 2);
;     SB_;
;     if (issue) { if (a2v) GLDS(q2, l_ + 16384); if (a3v) GLDS(q3, l_ + 24576); }
;     SB_;
;     MMF(a1, b1);
;     LOADF(a1, b1, 3);
;     SB_;
;     if (issue) { if (b0v) GLDS(s0, m_); if (b1v) GLDS(s1, m_ + 8192); }
;     SB_;
;     MMF(a0, b0);
;     SB_;
;     if (issue) { if (b2v) GLDS(s2, m_ + 16384); if (b3v) GLDS(s3, m_ + 24576); }
;     SB_;
;     MMF(a1, b1);
;     __builtin_amdgcn_s_setprio(0);
;   };
;   int sc_ = 0;
;   for (int kt = 0; kt < nk - 1; ++kt) {
;     SB_;
;     if (NST == 2) {
;       const int ko = (kt + 1) * 64;
;       compute(smem + (kt & 1) * STAGE, smem + ((kt + 1) & 1) * STAGE, true, pa0 + ko, pa1 + ko, pa2 + ko, pa3 + ko, pb0 + ko, pb1 + ko, pb2 + ko, pb3 + ko);
;       SB_;
;       wait_vm0(); bar_();
.LBB0_355:
	s_or_b64 exec, exec, s[4:5]
	s_waitcnt vmcnt(0)
	v_bfe_u32 v181, v8, 1, 3
	v_and_b32_e32 v222, 0xffffe000, v0
	v_bitop3_b32 v0, v2, v180, 7 bitop3:0x6c
	v_lshlrev_b32_e32 v216, 4, v0
	v_or_b32_e32 v224, v219, v222
	v_bitop3_b32 v1, v180, v181, 2 bitop3:0x36
	v_or_b32_e32 v0, v217, v216
	v_or_b32_e32 v4, v224, v216
	v_lshlrev_b32_e32 v188, 4, v1
	s_barrier
	v_or_b32_e32 v28, v217, v188
	v_or_b32_e32 v29, v224, v188
	ds_read_b128 v[20:23], v0
	ds_read_b128 v[12:15], v0 offset:4096
	ds_read_b128 v[8:11], v0 offset:8192
	ds_read_b128 v[0:3], v0 offset:12288
	ds_read_b128 v[16:19], v4 offset:32768
	ds_read_b128 v[4:7], v4 offset:36864
	ds_read_b128 v[172:175], v28
	ds_read_b128 v[168:171], v28 offset:4096
	ds_read_b128 v[160:163], v28 offset:8192
	ds_read_b128 v[128:131], v28 offset:12288
	ds_read_b128 v[164:167], v29 offset:32768
	ds_read_b128 v[132:135], v29 offset:36864
	v_bitop3_b32 v24, v180, v181, 4 bitop3:0x36
	v_lshlrev_b32_e32 v218, 4, v24
	s_setprio 1
	s_waitcnt lgkmcnt(0)
	v_mfma_f32_32x32x16_bf16 v[48:63], v[8:11], v[16:19], 0
	v_mfma_f32_32x32x16_bf16 v[32:47], v[8:11], v[4:7], 0
	v_add_u32_e32 v8, v217, v218
	ds_read_b128 v[156:159], v8
	ds_read_b128 v[152:155], v8 offset:4096
	ds_read_b128 v[140:143], v8 offset:8192
	ds_read_b128 v[136:139], v8 offset:12288
	v_add_u32_e32 v8, v224, v218
	ds_read_b128 v[148:151], v8 offset:32768
	ds_read_b128 v[144:147], v8 offset:36864
	v_mfma_f32_32x32x16_bf16 v[112:127], v[20:23], v[16:19], 0
	v_mfma_f32_32x32x16_bf16 v[96:111], v[20:23], v[4:7], 0
	v_mfma_f32_32x32x16_bf16 v[80:95], v[12:15], v[16:19], 0
	v_mfma_f32_32x32x16_bf16 v[64:79], v[12:15], v[4:7], 0
	v_mfma_f32_32x32x16_bf16 v[16:31], v[0:3], v[16:19], 0
	v_mfma_f32_32x32x16_bf16 v[0:15], v[0:3], v[4:7], 0
	v_bitop3_b32 v176, v180, v181, 6 bitop3:0x36
	v_lshlrev_b32_e32 v223, 4, v176
	v_mfma_f32_32x32x16_bf16 v[112:127], v[172:175], v[164:167], v[112:127]
	v_mfma_f32_32x32x16_bf16 v[96:111], v[172:175], v[132:135], v[96:111]
	v_mfma_f32_32x32x16_bf16 v[80:95], v[168:171], v[164:167], v[80:95]
	v_mfma_f32_32x32x16_bf16 v[64:79], v[168:171], v[132:135], v[64:79]
	v_add_u32_e32 v168, v224, v223
	v_mfma_f32_32x32x16_bf16 v[48:63], v[160:163], v[164:167], v[48:63]
	v_mfma_f32_32x32x16_bf16 v[32:47], v[160:163], v[132:135], v[32:47]
	v_add_u32_e32 v160, v217, v223
	v_mfma_f32_32x32x16_bf16 v[16:31], v[128:131], v[164:167], v[16:31]
	ds_read_b128 v[180:183], v160
	ds_read_b128 v[176:179], v160 offset:4096
	ds_read_b128 v[164:167], v160 offset:8192
	ds_read_b128 v[160:163], v160 offset:12288
	ds_read_b128 v[172:175], v168 offset:32768
	ds_read_b128 v[168:171], v168 offset:36864
	v_mfma_f32_32x32x16_bf16 v[0:15], v[128:131], v[132:135], v[0:15]
	s_waitcnt lgkmcnt(0)
	v_mfma_f32_32x32x16_bf16 v[112:127], v[156:159], v[148:151], v[112:127]
	v_mfma_f32_32x32x16_bf16 v[96:111], v[156:159], v[144:147], v[96:111]
	v_mfma_f32_32x32x16_bf16 v[80:95], v[152:155], v[148:151], v[80:95]
	v_mfma_f32_32x32x16_bf16 v[64:79], v[152:155], v[144:147], v[64:79]
	v_mfma_f32_32x32x16_bf16 v[48:63], v[140:143], v[148:151], v[48:63]
	v_mfma_f32_32x32x16_bf16 v[32:47], v[140:143], v[144:147], v[32:47]
	v_mfma_f32_32x32x16_bf16 v[16:31], v[136:139], v[148:151], v[16:31]
	v_mfma_f32_32x32x16_bf16 v[0:15], v[136:139], v[144:147], v[0:15]
	v_add3_u32 v196, v222, v219, s71
	v_mfma_f32_32x32x16_bf16 v[0:15], v[160:163], v[168:171], v[0:15]
	v_mfma_f32_32x32x16_bf16 v[112:127], v[180:183], v[172:175], v[112:127]
	v_mfma_f32_32x32x16_bf16 v[96:111], v[180:183], v[168:171], v[96:111]
	v_mfma_f32_32x32x16_bf16 v[80:95], v[176:179], v[172:175], v[80:95]
	v_mfma_f32_32x32x16_bf16 v[64:79], v[176:179], v[168:171], v[64:79]
	v_mfma_f32_32x32x16_bf16 v[48:63], v[164:167], v[172:175], v[48:63]
	v_mfma_f32_32x32x16_bf16 v[32:47], v[164:167], v[168:171], v[32:47]
	v_mfma_f32_32x32x16_bf16 v[16:31], v[160:163], v[172:175], v[16:31]
	s_setprio 0
	s_waitcnt vmcnt(0)
	s_barrier
	v_add_u32_e32 v197, 0x10000, v217
	v_add_u32_e32 v140, v197, v216
	v_add3_u32 v148, v196, v216, s76
	v_add_u32_e32 v164, v197, v188
	ds_read_b128 v[128:131], v140
	ds_read_b128 v[132:135], v140 offset:4096
	ds_read_b128 v[136:139], v140 offset:8192
	ds_read_b128 v[140:143], v140 offset:12288
	ds_read_b128 v[144:147], v148
	ds_read_b128 v[148:151], v148 offset:4096
	ds_read_b128 v[152:155], v164
	ds_read_b128 v[156:159], v164 offset:4096
	ds_read_b128 v[160:163], v164 offset:8192
	ds_read_b128 v[164:167], v164 offset:12288
	v_add3_u32 v172, v196, v188, s76
	ds_read_b128 v[168:171], v172
	ds_read_b128 v[172:175], v172 offset:4096
	s_setprio 1
	s_waitcnt lgkmcnt(0)
	v_mfma_f32_32x32x16_bf16 v[112:127], v[128:131], v[144:147], v[112:127]
	v_add3_u32 v180, v196, v218, s76
	v_mfma_f32_32x32x16_bf16 v[80:95], v[132:135], v[144:147], v[80:95]
	v_mfma_f32_32x32x16_bf16 v[48:63], v[136:139], v[144:147], v[48:63]
	v_mfma_f32_32x32x16_bf16 v[16:31], v[140:143], v[144:147], v[16:31]
	v_add_u32_e32 v144, v197, v218
	v_mfma_f32_32x32x16_bf16 v[0:15], v[140:143], v[148:151], v[0:15]
	v_mfma_f32_32x32x16_bf16 v[96:111], v[128:131], v[148:151], v[96:111]
	v_mfma_f32_32x32x16_bf16 v[64:79], v[132:135], v[148:151], v[64:79]
	v_mfma_f32_32x32x16_bf16 v[32:47], v[136:139], v[148:151], v[32:47]
	ds_read_b128 v[128:131], v144
	ds_read_b128 v[132:135], v144 offset:4096
	ds_read_b128 v[136:139], v144 offset:8192
	ds_read_b128 v[144:147], v144 offset:12288
	ds_read_b128 v[176:179], v180
	ds_read_b128 v[180:183], v180 offset:4096
	v_mfma_f32_32x32x16_bf16 v[80:95], v[156:159], v[168:171], v[80:95]
	v_mfma_f32_32x32x16_bf16 v[64:79], v[156:159], v[172:175], v[64:79]
	v_add_u32_e32 v156, v197, v223
	v_mfma_f32_32x32x16_bf16 v[0:15], v[164:167], v[172:175], v[0:15]
	v_mfma_f32_32x32x16_bf16 v[112:127], v[152:155], v[168:171], v[112:127]
	v_mfma_f32_32x32x16_bf16 v[96:111], v[152:155], v[172:175], v[96:111]
	ds_read_b128 v[140:143], v156
	ds_read_b128 v[148:151], v156 offset:4096
	ds_read_b128 v[152:155], v156 offset:8192
	ds_read_b128 v[156:159], v156 offset:12288
	v_mfma_f32_32x32x16_bf16 v[48:63], v[160:163], v[168:171], v[48:63]
	v_mfma_f32_32x32x16_bf16 v[16:31], v[164:167], v[168:171], v[16:31]
	v_add3_u32 v168, v196, v223, s76
	v_mfma_f32_32x32x16_bf16 v[32:47], v[160:163], v[172:175], v[32:47]
	ds_read_b128 v[160:163], v168
	ds_read_b128 v[168:171], v168 offset:4096
	s_waitcnt lgkmcnt(0)
; DI unsigned pk_bf16(float lo, float hi) { f32x2v v = {lo, hi}; bf16x2v b = __builtin_convertvector(v, bf16x2v); return __builtin_bit_cast(unsigned, b); }
; DI int tid_() { int t = threadIdx.x; asm volatile("" : "+v"(t)); return t; }
; DI void lds_sync() { wait_lgkm0(); bar_(); }
; template <int TM, int TN, int WM, int WN, class F>
; DI void stage_tile(const f32x16 (&acc)[TM][TN], char* tile, int pitch, F f) {
;   const int t = tid_(), lane = t & 63, w = t >> 6, r = lane & 31, hh = lane >> 5;
;   const int wm = w % WM, wn = w / WM;
; #pragma unroll
;   for (int tm = 0; tm < TM; ++tm)
; #pragma unroll
;     for (int tn = 0; tn < TN; ++tn) {
;       char* d = tile + (wn * TN * 32 + tn * 32 + r) * pitch + (wm * TM * 32 + tm * 32 + 4 * hh) * 2;
; #pragma unroll
;       for (int q = 0; q < 4; ++q) {
;         uint2 o; o.x = pk_bf16(f(acc[tm][tn][4 * q]), f(acc[tm][tn][4 * q + 1])); o.y = pk_bf16(f(acc[tm][tn][4 * q + 2]), f(acc[tm][tn][4 * q + 3]));
;         *(uint2*)(d + 16 * q) = o;
;       }
;     }
; }
; template <class RF>
; DI void copy_tile(const char* tile, int pitch, int rows, int lch, RF dst, int ch0, int ch1) {
;   const int t = tid_();
;   const int total = rows << lch;
;   for (int id = t; id < total; id += NTH) {
;     const int row = id >> lch, ch = id & ((1 << lch) - 1);
;     if (ch >= ch0 && ch < ch1) *(uint4*)(dst(row) + ch * 8) = *(const uint4*)(tile + row * pitch + ch * 16);
; DI void phase3(const Params& p, char* smem) {
;     ...
;       stage_tile<4, 2, 2, 4>(acc, smem, 528, [](float v) { return v; });
;       lds_sync();
;       bf16_t* dst0 = p.ABt + ((size_t)(b * 512 + g * 128)) * 4096 + tt * 256;
;       copy_tile(smem, 528, 256, 5, [&](int row) { return dst0 + (size_t)(row & 127) * 4096 + (row >> 7) * 2048; }, 0, 32);
	v_mfma_f32_32x32x16_bf16 v[0:15], v[144:147], v[180:183], v[0:15]
	v_mfma_f32_32x32x16_bf16 v[112:127], v[128:131], v[176:179], v[112:127]
	v_mfma_f32_32x32x16_bf16 v[96:111], v[128:131], v[180:183], v[96:111]
	v_mfma_f32_32x32x16_bf16 v[80:95], v[132:135], v[176:179], v[80:95]
	v_mfma_f32_32x32x16_bf16 v[64:79], v[132:135], v[180:183], v[64:79]
	v_mfma_f32_32x32x16_bf16 v[48:63], v[136:139], v[176:179], v[48:63]
	v_mfma_f32_32x32x16_bf16 v[32:47], v[136:139], v[180:183], v[32:47]
	v_mfma_f32_32x32x16_bf16 v[16:31], v[144:147], v[176:179], v[16:31]
	v_mfma_f32_32x32x16_bf16 v[0:15], v[156:159], v[168:171], v[0:15]
	v_mfma_f32_32x32x16_bf16 v[112:127], v[140:143], v[160:163], v[112:127]
	v_mfma_f32_32x32x16_bf16 v[96:111], v[140:143], v[168:171], v[96:111]
	v_mfma_f32_32x32x16_bf16 v[80:95], v[148:151], v[160:163], v[80:95]
	v_mfma_f32_32x32x16_bf16 v[64:79], v[148:151], v[168:171], v[64:79]
	v_mfma_f32_32x32x16_bf16 v[48:63], v[152:155], v[160:163], v[48:63]
	v_mfma_f32_32x32x16_bf16 v[32:47], v[152:155], v[168:171], v[32:47]
	v_mfma_f32_32x32x16_bf16 v[16:31], v[156:159], v[160:163], v[16:31]
	s_setprio 0
	v_mov_b32_e32 v128, v220
	s_waitcnt lgkmcnt(0)
	s_barrier
	s_nop 2
	v_cvt_pk_bf16_f32 v112, v112, v113
	v_ashrrev_i32_e32 v129, 6, v128
	v_lshrrev_b32_e32 v131, 31, v128
	v_add_u32_e32 v131, v129, v131
	v_and_b32_e32 v130, 31, v128
	v_and_b32_e32 v132, 0xfffffe, v131
	v_lshrrev_b32_e32 v128, 2, v128
	v_sub_u32_e32 v129, v129, v132
	v_lshlrev_b32_e32 v131, 5, v131
	v_and_b32_e32 v128, 8, v128
	v_and_or_b32 v130, v131, s77, v130
	v_lshl_or_b32 v128, v129, 8, v128
	v_mad_u64_u32 v[128:129], s[4:5], v130, s78, v[128:129]
	v_cvt_pk_bf16_f32 v113, v114, v115
	v_cvt_pk_bf16_f32 v114, v116, v117
	v_cvt_pk_bf16_f32 v115, v118, v119
	v_cvt_pk_bf16_f32 v96, v96, v97
	v_cvt_pk_bf16_f32 v97, v98, v99
	v_cvt_pk_bf16_f32 v98, v100, v101
	v_cvt_pk_bf16_f32 v99, v102, v103
	v_add_u32_e32 v100, 0x4000, v128
	v_cvt_pk_bf16_f32 v80, v80, v81
	v_cvt_pk_bf16_f32 v81, v82, v83
	v_cvt_pk_bf16_f32 v82, v84, v85
	v_cvt_pk_bf16_f32 v83, v86, v87
	v_cvt_pk_bf16_f32 v64, v64, v65
	v_cvt_pk_bf16_f32 v65, v66, v67
	v_cvt_pk_bf16_f32 v66, v68, v69
	v_cvt_pk_bf16_f32 v67, v70, v71
	v_cvt_pk_bf16_f32 v48, v48, v49
	v_cvt_pk_bf16_f32 v49, v50, v51
	v_cvt_pk_bf16_f32 v50, v52, v53
	v_cvt_pk_bf16_f32 v51, v54, v55
	v_cvt_pk_bf16_f32 v32, v32, v33
	v_cvt_pk_bf16_f32 v33, v34, v35
	v_cvt_pk_bf16_f32 v34, v36, v37
	v_cvt_pk_bf16_f32 v35, v38, v39
	v_cvt_pk_bf16_f32 v16, v16, v17
	v_cvt_pk_bf16_f32 v17, v18, v19
	v_cvt_pk_bf16_f32 v18, v20, v21
	v_cvt_pk_bf16_f32 v19, v22, v23
	v_cvt_pk_bf16_f32 v0, v0, v1
	v_cvt_pk_bf16_f32 v1, v2, v3
	v_cvt_pk_bf16_f32 v2, v4, v5
	v_cvt_pk_bf16_f32 v3, v6, v7
	s_waitcnt vmcnt(0)
	ds_write2_b64 v128, v[112:113], v[114:115] offset1:2
	v_cvt_pk_bf16_f32 v112, v120, v121
	v_cvt_pk_bf16_f32 v113, v122, v123
	v_cvt_pk_bf16_f32 v114, v124, v125
	v_cvt_pk_bf16_f32 v115, v126, v127
	ds_write2_b64 v100, v[96:97], v[98:99] offset0:64 offset1:66
	v_cvt_pk_bf16_f32 v96, v104, v105
	v_cvt_pk_bf16_f32 v97, v106, v107
	v_cvt_pk_bf16_f32 v98, v108, v109
	v_cvt_pk_bf16_f32 v99, v110, v111
	ds_write2_b64 v128, v[80:81], v[82:83] offset0:8 offset1:10
	v_cvt_pk_bf16_f32 v80, v88, v89
	v_cvt_pk_bf16_f32 v81, v90, v91
	v_cvt_pk_bf16_f32 v82, v92, v93
	v_cvt_pk_bf16_f32 v83, v94, v95
	ds_write2_b64 v100, v[64:65], v[66:67] offset0:72 offset1:74
	v_cvt_pk_bf16_f32 v64, v72, v73
	v_cvt_pk_bf16_f32 v65, v74, v75
	v_cvt_pk_bf16_f32 v66, v76, v77
	v_cvt_pk_bf16_f32 v67, v78, v79
	ds_write2_b64 v128, v[48:49], v[50:51] offset0:16 offset1:18
	v_cvt_pk_bf16_f32 v48, v56, v57
	v_cvt_pk_bf16_f32 v49, v58, v59
	v_cvt_pk_bf16_f32 v50, v60, v61
	v_cvt_pk_bf16_f32 v51, v62, v63
	ds_write2_b64 v100, v[32:33], v[34:35] offset0:80 offset1:82
	v_cvt_pk_bf16_f32 v32, v40, v41
	v_cvt_pk_bf16_f32 v33, v42, v43
	v_cvt_pk_bf16_f32 v34, v44, v45
	v_cvt_pk_bf16_f32 v35, v46, v47
	ds_write2_b64 v128, v[16:17], v[18:19] offset0:24 offset1:26
	v_cvt_pk_bf16_f32 v16, v24, v25
	v_cvt_pk_bf16_f32 v17, v26, v27
	v_cvt_pk_bf16_f32 v18, v28, v29
	v_cvt_pk_bf16_f32 v19, v30, v31
	ds_write2_b64 v100, v[0:1], v[2:3] offset0:88 offset1:90
	v_cvt_pk_bf16_f32 v0, v8, v9
	v_cvt_pk_bf16_f32 v1, v10, v11
	v_cvt_pk_bf16_f32 v2, v12, v13
	v_cvt_pk_bf16_f32 v3, v14, v15
	ds_write2_b64 v128, v[112:113], v[114:115] offset0:4 offset1:6
	ds_write2_b64 v100, v[96:97], v[98:99] offset0:68 offset1:70
	ds_write2_b64 v128, v[80:81], v[82:83] offset0:12 offset1:14
	ds_write2_b64 v100, v[64:65], v[66:67] offset0:76 offset1:78
	ds_write2_b64 v128, v[48:49], v[50:51] offset0:20 offset1:22
	ds_write2_b64 v100, v[32:33], v[34:35] offset0:84 offset1:86
	ds_write2_b64 v128, v[16:17], v[18:19] offset0:28 offset1:30
	ds_write2_b64 v100, v[0:1], v[2:3] offset0:92 offset1:94
	s_waitcnt lgkmcnt(0)
	v_mov_b32_e32 v1, v220
	s_barrier
	s_nop 0
	v_cmp_gt_i32_e32 vcc, s69, v1
	s_and_saveexec_b64 s[4:5], vcc
	s_cbranch_execz .LBB0_358
	s_lshl_b32 s6, s13, 9
	s_or_b32 s42, s6, s14
	s_lshl_b64 s[6:7], s[42:43], 13
	s_add_u32 s6, s34, s6
	s_addc_u32 s7, s35, s7
	s_lshl_b32 s8, s12, 1
	v_and_b32_e32 v2, 31, v1
	s_add_u32 s6, s6, s8
	v_lshlrev_b32_e32 v0, 4, v2
	v_lshlrev_b32_e32 v2, 3, v2
	s_addc_u32 s7, s7, 0
	s_mov_b64 s[8:9], 0
	v_lshlrev_b32_e32 v2, 1, v2
